# v28 plus nt hint on both sides of the K-split partial-tile stream (residual GEMM split-path stores, norm fold-path loads)
# speedup vs baseline: 1.0074x; 1.0074x over previous
.Lepi_r_split:
	s_lshl_b32 s3, s65, 8
	s_ashr_i32 s85, s84, 31
	s_add_i32 s30, s3, 0xffffc000
	s_ashr_i32 s31, s30, 31
	s_lshl_b64 s[34:35], s[84:85], 22
	s_add_u32 s3, s93, s34
	s_addc_u32 s24, s53, s35
	s_lshl_b64 s[30:31], s[30:31], 12
	s_add_u32 s30, s3, s30
	s_addc_u32 s31, s24, s31
	s_waitcnt vmcnt(0)
	v_mul_f32_e32 v132, s88, v132
	v_mul_f32_e32 v133, s88, v133
	v_mul_f32_e32 v134, s88, v134
	v_mul_f32_e32 v135, s88, v135
	v_mul_f32_e32 v136, s88, v136
	v_mul_f32_e32 v137, s88, v137
	v_mul_f32_e32 v138, s88, v138
	v_mul_f32_e32 v139, s88, v139
	v_mul_f32_e32 v140, s88, v140
	v_mul_f32_e32 v141, s88, v141
	v_mul_f32_e32 v142, s88, v142
	v_mul_f32_e32 v143, s88, v143
	v_mul_f32_e32 v168, s88, v168
	v_mul_f32_e32 v169, s88, v169
	v_mul_f32_e32 v170, s88, v170
	v_mul_f32_e32 v171, s88, v171
	v_cmp_gt_u32_e32 vcc, 8, v164
	v_cndmask_b32_e32 v132, v136, v132, vcc
	v_cndmask_b32_e32 v133, v137, v133, vcc
	v_cndmask_b32_e32 v134, v138, v134, vcc
	v_cndmask_b32_e32 v135, v139, v135, vcc
	v_cndmask_b32_e32 v140, v168, v140, vcc
	v_cndmask_b32_e32 v141, v169, v141, vcc
	v_cndmask_b32_e32 v142, v170, v142, vcc
	v_cndmask_b32_e32 v143, v171, v143, vcc
	v_cndmask_b32_dpp v232, v124, v128, vcc row_ror:8 row_mask:0xf bank_mask:0xf
	v_cndmask_b32_dpp v233, v125, v129, vcc row_ror:8 row_mask:0xf bank_mask:0xf
	v_cndmask_b32_dpp v234, v126, v130, vcc row_ror:8 row_mask:0xf bank_mask:0xf
	v_cndmask_b32_dpp v235, v127, v131, vcc row_ror:8 row_mask:0xf bank_mask:0xf
	s_not_b64 vcc, vcc
	v_cndmask_b32_dpp v124, v128, v124, vcc row_ror:8 row_mask:0xf bank_mask:0xf
	v_cndmask_b32_dpp v125, v129, v125, vcc row_ror:8 row_mask:0xf bank_mask:0xf
	v_cndmask_b32_dpp v126, v130, v126, vcc row_ror:8 row_mask:0xf bank_mask:0xf
	v_cndmask_b32_dpp v127, v131, v127, vcc row_ror:8 row_mask:0xf bank_mask:0xf
	s_not_b64 vcc, vcc
	v_pk_mul_f32 v[128:129], v[132:133], v[232:233]
	v_pk_mul_f32 v[130:131], v[134:135], v[234:235]
	v_pk_mul_f32 v[124:125], v[132:133], v[124:125]
	v_pk_mul_f32 v[126:127], v[134:135], v[126:127]
	global_store_dwordx4 v162, v[128:131], s[30:31] nt
	global_store_dwordx4 v163, v[124:127], s[30:31] nt
	v_cndmask_b32_dpp v232, v116, v120, vcc row_ror:8 row_mask:0xf bank_mask:0xf
	v_cndmask_b32_dpp v233, v117, v121, vcc row_ror:8 row_mask:0xf bank_mask:0xf
	v_cndmask_b32_dpp v234, v118, v122, vcc row_ror:8 row_mask:0xf bank_mask:0xf
	v_cndmask_b32_dpp v235, v119, v123, vcc row_ror:8 row_mask:0xf bank_mask:0xf
	s_not_b64 vcc, vcc
	v_cndmask_b32_dpp v116, v120, v116, vcc row_ror:8 row_mask:0xf bank_mask:0xf
	v_cndmask_b32_dpp v117, v121, v117, vcc row_ror:8 row_mask:0xf bank_mask:0xf
	v_cndmask_b32_dpp v118, v122, v118, vcc row_ror:8 row_mask:0xf bank_mask:0xf
	v_cndmask_b32_dpp v119, v123, v119, vcc row_ror:8 row_mask:0xf bank_mask:0xf
	s_not_b64 vcc, vcc
	v_pk_mul_f32 v[120:121], v[140:141], v[232:233]
	v_pk_mul_f32 v[122:123], v[142:143], v[234:235]
	v_pk_mul_f32 v[116:117], v[140:141], v[116:117]
	v_pk_mul_f32 v[118:119], v[142:143], v[118:119]
	global_store_dwordx4 v162, v[120:123], s[30:31] offset:512 nt
	global_store_dwordx4 v163, v[116:119], s[30:31] offset:512 nt
	s_add_u32 s30, s30, 0x10000
	s_addc_u32 s31, s31, 0
	v_cndmask_b32_dpp v232, v108, v112, vcc row_ror:8 row_mask:0xf bank_mask:0xf
	v_cndmask_b32_dpp v233, v109, v113, vcc row_ror:8 row_mask:0xf bank_mask:0xf
	v_cndmask_b32_dpp v234, v110, v114, vcc row_ror:8 row_mask:0xf bank_mask:0xf
	v_cndmask_b32_dpp v235, v111, v115, vcc row_ror:8 row_mask:0xf bank_mask:0xf
	s_not_b64 vcc, vcc
	v_cndmask_b32_dpp v108, v112, v108, vcc row_ror:8 row_mask:0xf bank_mask:0xf
	v_cndmask_b32_dpp v109, v113, v109, vcc row_ror:8 row_mask:0xf bank_mask:0xf
	v_cndmask_b32_dpp v110, v114, v110, vcc row_ror:8 row_mask:0xf bank_mask:0xf
	v_cndmask_b32_dpp v111, v115, v111, vcc row_ror:8 row_mask:0xf bank_mask:0xf
	s_not_b64 vcc, vcc
	v_pk_mul_f32 v[112:113], v[132:133], v[232:233]
	v_pk_mul_f32 v[114:115], v[134:135], v[234:235]
	v_pk_mul_f32 v[108:109], v[132:133], v[108:109]
	v_pk_mul_f32 v[110:111], v[134:135], v[110:111]
	global_store_dwordx4 v162, v[112:115], s[30:31] nt
	global_store_dwordx4 v163, v[108:111], s[30:31] nt
	v_cndmask_b32_dpp v232, v100, v104, vcc row_ror:8 row_mask:0xf bank_mask:0xf
	v_cndmask_b32_dpp v233, v101, v105, vcc row_ror:8 row_mask:0xf bank_mask:0xf
	v_cndmask_b32_dpp v234, v102, v106, vcc row_ror:8 row_mask:0xf bank_mask:0xf
	v_cndmask_b32_dpp v235, v103, v107, vcc row_ror:8 row_mask:0xf bank_mask:0xf
	s_not_b64 vcc, vcc
	v_cndmask_b32_dpp v100, v104, v100, vcc row_ror:8 row_mask:0xf bank_mask:0xf
	v_cndmask_b32_dpp v101, v105, v101, vcc row_ror:8 row_mask:0xf bank_mask:0xf
	v_cndmask_b32_dpp v102, v106, v102, vcc row_ror:8 row_mask:0xf bank_mask:0xf
	v_cndmask_b32_dpp v103, v107, v103, vcc row_ror:8 row_mask:0xf bank_mask:0xf
	s_not_b64 vcc, vcc
	v_pk_mul_f32 v[104:105], v[140:141], v[232:233]
	v_pk_mul_f32 v[106:107], v[142:143], v[234:235]
	v_pk_mul_f32 v[100:101], v[140:141], v[100:101]
	v_pk_mul_f32 v[102:103], v[142:143], v[102:103]
	global_store_dwordx4 v162, v[104:107], s[30:31] offset:512 nt
	global_store_dwordx4 v163, v[100:103], s[30:31] offset:512 nt
	s_add_u32 s30, s30, 0x10000
	s_addc_u32 s31, s31, 0
	v_cndmask_b32_dpp v232, v92, v96, vcc row_ror:8 row_mask:0xf bank_mask:0xf
	v_cndmask_b32_dpp v233, v93, v97, vcc row_ror:8 row_mask:0xf bank_mask:0xf
	v_cndmask_b32_dpp v234, v94, v98, vcc row_ror:8 row_mask:0xf bank_mask:0xf
	v_cndmask_b32_dpp v235, v95, v99, vcc row_ror:8 row_mask:0xf bank_mask:0xf
	s_not_b64 vcc, vcc
	v_cndmask_b32_dpp v92, v96, v92, vcc row_ror:8 row_mask:0xf bank_mask:0xf
	v_cndmask_b32_dpp v93, v97, v93, vcc row_ror:8 row_mask:0xf bank_mask:0xf
	v_cndmask_b32_dpp v94, v98, v94, vcc row_ror:8 row_mask:0xf bank_mask:0xf
	v_cndmask_b32_dpp v95, v99, v95, vcc row_ror:8 row_mask:0xf bank_mask:0xf
	s_not_b64 vcc, vcc
	v_pk_mul_f32 v[96:97], v[132:133], v[232:233]
	v_pk_mul_f32 v[98:99], v[134:135], v[234:235]
	v_pk_mul_f32 v[92:93], v[132:133], v[92:93]
	v_pk_mul_f32 v[94:95], v[134:135], v[94:95]
	global_store_dwordx4 v162, v[96:99], s[30:31] nt
	global_store_dwordx4 v163, v[92:95], s[30:31] nt
	v_cndmask_b32_dpp v232, v84, v88, vcc row_ror:8 row_mask:0xf bank_mask:0xf
	v_cndmask_b32_dpp v233, v85, v89, vcc row_ror:8 row_mask:0xf bank_mask:0xf
	v_cndmask_b32_dpp v234, v86, v90, vcc row_ror:8 row_mask:0xf bank_mask:0xf
	v_cndmask_b32_dpp v235, v87, v91, vcc row_ror:8 row_mask:0xf bank_mask:0xf
	s_not_b64 vcc, vcc
	v_cndmask_b32_dpp v84, v88, v84, vcc row_ror:8 row_mask:0xf bank_mask:0xf
	v_cndmask_b32_dpp v85, v89, v85, vcc row_ror:8 row_mask:0xf bank_mask:0xf
	v_cndmask_b32_dpp v86, v90, v86, vcc row_ror:8 row_mask:0xf bank_mask:0xf
	v_cndmask_b32_dpp v87, v91, v87, vcc row_ror:8 row_mask:0xf bank_mask:0xf
	s_not_b64 vcc, vcc
	v_pk_mul_f32 v[88:89], v[140:141], v[232:233]
	v_pk_mul_f32 v[90:91], v[142:143], v[234:235]
	v_pk_mul_f32 v[84:85], v[140:141], v[84:85]
	v_pk_mul_f32 v[86:87], v[142:143], v[86:87]
	global_store_dwordx4 v162, v[88:91], s[30:31] offset:512 nt
	global_store_dwordx4 v163, v[84:87], s[30:31] offset:512 nt
	s_add_u32 s30, s30, 0x10000
	s_addc_u32 s31, s31, 0
	v_cndmask_b32_dpp v232, v76, v80, vcc row_ror:8 row_mask:0xf bank_mask:0xf
	v_cndmask_b32_dpp v233, v77, v81, vcc row_ror:8 row_mask:0xf bank_mask:0xf
	v_cndmask_b32_dpp v234, v78, v82, vcc row_ror:8 row_mask:0xf bank_mask:0xf
	v_cndmask_b32_dpp v235, v79, v83, vcc row_ror:8 row_mask:0xf bank_mask:0xf
	s_not_b64 vcc, vcc
	v_cndmask_b32_dpp v76, v80, v76, vcc row_ror:8 row_mask:0xf bank_mask:0xf
	v_cndmask_b32_dpp v77, v81, v77, vcc row_ror:8 row_mask:0xf bank_mask:0xf
	v_cndmask_b32_dpp v78, v82, v78, vcc row_ror:8 row_mask:0xf bank_mask:0xf
	v_cndmask_b32_dpp v79, v83, v79, vcc row_ror:8 row_mask:0xf bank_mask:0xf
	s_not_b64 vcc, vcc
	v_pk_mul_f32 v[80:81], v[132:133], v[232:233]
	v_pk_mul_f32 v[82:83], v[134:135], v[234:235]
	v_pk_mul_f32 v[76:77], v[132:133], v[76:77]
	v_pk_mul_f32 v[78:79], v[134:135], v[78:79]
	global_store_dwordx4 v162, v[80:83], s[30:31] nt
	global_store_dwordx4 v163, v[76:79], s[30:31] nt
	v_cndmask_b32_dpp v232, v68, v72, vcc row_ror:8 row_mask:0xf bank_mask:0xf
	v_cndmask_b32_dpp v233, v69, v73, vcc row_ror:8 row_mask:0xf bank_mask:0xf
	v_cndmask_b32_dpp v234, v70, v74, vcc row_ror:8 row_mask:0xf bank_mask:0xf
	v_cndmask_b32_dpp v235, v71, v75, vcc row_ror:8 row_mask:0xf bank_mask:0xf
	s_not_b64 vcc, vcc
	v_cndmask_b32_dpp v68, v72, v68, vcc row_ror:8 row_mask:0xf bank_mask:0xf
	v_cndmask_b32_dpp v69, v73, v69, vcc row_ror:8 row_mask:0xf bank_mask:0xf
	v_cndmask_b32_dpp v70, v74, v70, vcc row_ror:8 row_mask:0xf bank_mask:0xf
	v_cndmask_b32_dpp v71, v75, v71, vcc row_ror:8 row_mask:0xf bank_mask:0xf
	s_not_b64 vcc, vcc
	v_pk_mul_f32 v[72:73], v[140:141], v[232:233]
	v_pk_mul_f32 v[74:75], v[142:143], v[234:235]
	v_pk_mul_f32 v[68:69], v[140:141], v[68:69]
	v_pk_mul_f32 v[70:71], v[142:143], v[70:71]
	global_store_dwordx4 v162, v[72:75], s[30:31] offset:512 nt
	global_store_dwordx4 v163, v[68:71], s[30:31] offset:512 nt
	s_add_u32 s30, s30, 0x50000
	s_addc_u32 s31, s31, 0
	v_cndmask_b32_dpp v232, v58, v62, vcc row_ror:8 row_mask:0xf bank_mask:0xf
	v_cndmask_b32_dpp v233, v59, v63, vcc row_ror:8 row_mask:0xf bank_mask:0xf
	v_cndmask_b32_dpp v234, v60, v64, vcc row_ror:8 row_mask:0xf bank_mask:0xf
	v_cndmask_b32_dpp v235, v61, v65, vcc row_ror:8 row_mask:0xf bank_mask:0xf
	s_not_b64 vcc, vcc
	v_cndmask_b32_dpp v58, v62, v58, vcc row_ror:8 row_mask:0xf bank_mask:0xf
	v_cndmask_b32_dpp v59, v63, v59, vcc row_ror:8 row_mask:0xf bank_mask:0xf
	v_cndmask_b32_dpp v60, v64, v60, vcc row_ror:8 row_mask:0xf bank_mask:0xf
	v_cndmask_b32_dpp v61, v65, v61, vcc row_ror:8 row_mask:0xf bank_mask:0xf
	s_not_b64 vcc, vcc
	v_pk_mul_f32 v[62:63], v[132:133], v[232:233]
	v_pk_mul_f32 v[64:65], v[134:135], v[234:235]
	v_pk_mul_f32 v[58:59], v[132:133], v[58:59]
	v_pk_mul_f32 v[60:61], v[134:135], v[60:61]
	global_store_dwordx4 v162, v[62:65], s[30:31] nt
	global_store_dwordx4 v163, v[58:61], s[30:31] nt
	v_cndmask_b32_dpp v232, v50, v54, vcc row_ror:8 row_mask:0xf bank_mask:0xf
	v_cndmask_b32_dpp v233, v51, v55, vcc row_ror:8 row_mask:0xf bank_mask:0xf
	v_cndmask_b32_dpp v234, v52, v56, vcc row_ror:8 row_mask:0xf bank_mask:0xf
	v_cndmask_b32_dpp v235, v53, v57, vcc row_ror:8 row_mask:0xf bank_mask:0xf
	s_not_b64 vcc, vcc
	v_cndmask_b32_dpp v50, v54, v50, vcc row_ror:8 row_mask:0xf bank_mask:0xf
	v_cndmask_b32_dpp v51, v55, v51, vcc row_ror:8 row_mask:0xf bank_mask:0xf
	v_cndmask_b32_dpp v52, v56, v52, vcc row_ror:8 row_mask:0xf bank_mask:0xf
	v_cndmask_b32_dpp v53, v57, v53, vcc row_ror:8 row_mask:0xf bank_mask:0xf
	s_not_b64 vcc, vcc
	v_pk_mul_f32 v[54:55], v[140:141], v[232:233]
	v_pk_mul_f32 v[56:57], v[142:143], v[234:235]
	v_pk_mul_f32 v[50:51], v[140:141], v[50:51]
	v_pk_mul_f32 v[52:53], v[142:143], v[52:53]
	global_store_dwordx4 v162, v[54:57], s[30:31] offset:512 nt
	global_store_dwordx4 v163, v[50:53], s[30:31] offset:512 nt
	s_add_u32 s30, s30, 0x10000
	s_addc_u32 s31, s31, 0
	v_cndmask_b32_dpp v232, v42, v46, vcc row_ror:8 row_mask:0xf bank_mask:0xf
	v_cndmask_b32_dpp v233, v43, v47, vcc row_ror:8 row_mask:0xf bank_mask:0xf
	v_cndmask_b32_dpp v234, v44, v48, vcc row_ror:8 row_mask:0xf bank_mask:0xf
	v_cndmask_b32_dpp v235, v45, v49, vcc row_ror:8 row_mask:0xf bank_mask:0xf
	s_not_b64 vcc, vcc
	v_cndmask_b32_dpp v42, v46, v42, vcc row_ror:8 row_mask:0xf bank_mask:0xf
	v_cndmask_b32_dpp v43, v47, v43, vcc row_ror:8 row_mask:0xf bank_mask:0xf
	v_cndmask_b32_dpp v44, v48, v44, vcc row_ror:8 row_mask:0xf bank_mask:0xf
	v_cndmask_b32_dpp v45, v49, v45, vcc row_ror:8 row_mask:0xf bank_mask:0xf
	s_not_b64 vcc, vcc
	v_pk_mul_f32 v[46:47], v[132:133], v[232:233]
	v_pk_mul_f32 v[48:49], v[134:135], v[234:235]
	v_pk_mul_f32 v[42:43], v[132:133], v[42:43]
	v_pk_mul_f32 v[44:45], v[134:135], v[44:45]
	global_store_dwordx4 v162, v[46:49], s[30:31] nt
	global_store_dwordx4 v163, v[42:45], s[30:31] nt
	v_cndmask_b32_dpp v232, v34, v38, vcc row_ror:8 row_mask:0xf bank_mask:0xf
	v_cndmask_b32_dpp v233, v35, v39, vcc row_ror:8 row_mask:0xf bank_mask:0xf
	v_cndmask_b32_dpp v234, v36, v40, vcc row_ror:8 row_mask:0xf bank_mask:0xf
	v_cndmask_b32_dpp v235, v37, v41, vcc row_ror:8 row_mask:0xf bank_mask:0xf
	s_not_b64 vcc, vcc
	v_cndmask_b32_dpp v34, v38, v34, vcc row_ror:8 row_mask:0xf bank_mask:0xf
	v_cndmask_b32_dpp v35, v39, v35, vcc row_ror:8 row_mask:0xf bank_mask:0xf
	v_cndmask_b32_dpp v36, v40, v36, vcc row_ror:8 row_mask:0xf bank_mask:0xf
	v_cndmask_b32_dpp v37, v41, v37, vcc row_ror:8 row_mask:0xf bank_mask:0xf
	s_not_b64 vcc, vcc
	v_pk_mul_f32 v[38:39], v[140:141], v[232:233]
	v_pk_mul_f32 v[40:41], v[142:143], v[234:235]
	v_pk_mul_f32 v[34:35], v[140:141], v[34:35]
	v_pk_mul_f32 v[36:37], v[142:143], v[36:37]
	global_store_dwordx4 v162, v[38:41], s[30:31] offset:512 nt
	global_store_dwordx4 v163, v[34:37], s[30:31] offset:512 nt
	s_add_u32 s30, s30, 0x10000
	s_addc_u32 s31, s31, 0
	v_cndmask_b32_dpp v232, v26, v30, vcc row_ror:8 row_mask:0xf bank_mask:0xf
	v_cndmask_b32_dpp v233, v27, v31, vcc row_ror:8 row_mask:0xf bank_mask:0xf
	v_cndmask_b32_dpp v234, v28, v32, vcc row_ror:8 row_mask:0xf bank_mask:0xf
	v_cndmask_b32_dpp v235, v29, v33, vcc row_ror:8 row_mask:0xf bank_mask:0xf
	s_not_b64 vcc, vcc
	v_cndmask_b32_dpp v26, v30, v26, vcc row_ror:8 row_mask:0xf bank_mask:0xf
	v_cndmask_b32_dpp v27, v31, v27, vcc row_ror:8 row_mask:0xf bank_mask:0xf
	v_cndmask_b32_dpp v28, v32, v28, vcc row_ror:8 row_mask:0xf bank_mask:0xf
	v_cndmask_b32_dpp v29, v33, v29, vcc row_ror:8 row_mask:0xf bank_mask:0xf
	s_not_b64 vcc, vcc
	v_pk_mul_f32 v[30:31], v[132:133], v[232:233]
	v_pk_mul_f32 v[32:33], v[134:135], v[234:235]
	v_pk_mul_f32 v[26:27], v[132:133], v[26:27]
	v_pk_mul_f32 v[28:29], v[134:135], v[28:29]
	global_store_dwordx4 v162, v[30:33], s[30:31] nt
	global_store_dwordx4 v163, v[26:29], s[30:31] nt
	v_cndmask_b32_dpp v232, v18, v22, vcc row_ror:8 row_mask:0xf bank_mask:0xf
	v_cndmask_b32_dpp v233, v19, v23, vcc row_ror:8 row_mask:0xf bank_mask:0xf
	v_cndmask_b32_dpp v234, v20, v24, vcc row_ror:8 row_mask:0xf bank_mask:0xf
	v_cndmask_b32_dpp v235, v21, v25, vcc row_ror:8 row_mask:0xf bank_mask:0xf
	s_not_b64 vcc, vcc
	v_cndmask_b32_dpp v18, v22, v18, vcc row_ror:8 row_mask:0xf bank_mask:0xf
	v_cndmask_b32_dpp v19, v23, v19, vcc row_ror:8 row_mask:0xf bank_mask:0xf
	v_cndmask_b32_dpp v20, v24, v20, vcc row_ror:8 row_mask:0xf bank_mask:0xf
	v_cndmask_b32_dpp v21, v25, v21, vcc row_ror:8 row_mask:0xf bank_mask:0xf
	s_not_b64 vcc, vcc
	v_pk_mul_f32 v[22:23], v[140:141], v[232:233]
	v_pk_mul_f32 v[24:25], v[142:143], v[234:235]
	v_pk_mul_f32 v[18:19], v[140:141], v[18:19]
	v_pk_mul_f32 v[20:21], v[142:143], v[20:21]
	global_store_dwordx4 v162, v[22:25], s[30:31] offset:512 nt
	global_store_dwordx4 v163, v[18:21], s[30:31] offset:512 nt
	s_add_u32 s30, s30, 0x10000
	s_addc_u32 s31, s31, 0
	v_cndmask_b32_dpp v232, v10, v14, vcc row_ror:8 row_mask:0xf bank_mask:0xf
	v_cndmask_b32_dpp v233, v11, v15, vcc row_ror:8 row_mask:0xf bank_mask:0xf
	v_cndmask_b32_dpp v234, v12, v16, vcc row_ror:8 row_mask:0xf bank_mask:0xf
	v_cndmask_b32_dpp v235, v13, v17, vcc row_ror:8 row_mask:0xf bank_mask:0xf
	s_not_b64 vcc, vcc
	v_cndmask_b32_dpp v10, v14, v10, vcc row_ror:8 row_mask:0xf bank_mask:0xf
	v_cndmask_b32_dpp v11, v15, v11, vcc row_ror:8 row_mask:0xf bank_mask:0xf
	v_cndmask_b32_dpp v12, v16, v12, vcc row_ror:8 row_mask:0xf bank_mask:0xf
	v_cndmask_b32_dpp v13, v17, v13, vcc row_ror:8 row_mask:0xf bank_mask:0xf
	s_not_b64 vcc, vcc
	v_pk_mul_f32 v[14:15], v[132:133], v[232:233]
	v_pk_mul_f32 v[16:17], v[134:135], v[234:235]
	v_pk_mul_f32 v[10:11], v[132:133], v[10:11]
	v_pk_mul_f32 v[12:13], v[134:135], v[12:13]
	global_store_dwordx4 v162, v[14:17], s[30:31] nt
	global_store_dwordx4 v163, v[10:13], s[30:31] nt
	v_cndmask_b32_dpp v232, v2, v6, vcc row_ror:8 row_mask:0xf bank_mask:0xf
	v_cndmask_b32_dpp v233, v3, v7, vcc row_ror:8 row_mask:0xf bank_mask:0xf
	v_cndmask_b32_dpp v234, v4, v8, vcc row_ror:8 row_mask:0xf bank_mask:0xf
	v_cndmask_b32_dpp v235, v5, v9, vcc row_ror:8 row_mask:0xf bank_mask:0xf
	s_not_b64 vcc, vcc
	v_cndmask_b32_dpp v2, v6, v2, vcc row_ror:8 row_mask:0xf bank_mask:0xf
	v_cndmask_b32_dpp v3, v7, v3, vcc row_ror:8 row_mask:0xf bank_mask:0xf
	v_cndmask_b32_dpp v4, v8, v4, vcc row_ror:8 row_mask:0xf bank_mask:0xf
	v_cndmask_b32_dpp v5, v9, v5, vcc row_ror:8 row_mask:0xf bank_mask:0xf
	s_not_b64 vcc, vcc
	v_pk_mul_f32 v[6:7], v[140:141], v[232:233]
	v_pk_mul_f32 v[8:9], v[142:143], v[234:235]
	v_pk_mul_f32 v[2:3], v[140:141], v[2:3]
	v_pk_mul_f32 v[4:5], v[142:143], v[4:5]
	global_store_dwordx4 v162, v[6:9], s[30:31] offset:512 nt
	global_store_dwordx4 v163, v[2:5], s[30:31] offset:512 nt

.LBB0_511:
	v_cndmask_b32_e64 v26, 0, 1, s[0:1]
	s_andn2_b64 vcc, exec, s[4:5]
	v_cmp_ne_u32_e64 s[38:39], 1, v26
	s_cbranch_vccnz .LBB0_517
	v_lshl_add_u64 v[102:103], s[78:79], 2, v[130:131]
	v_add_co_u32_e32 v14, vcc, 0x400000, v102
	s_mov_b64 s[28:29], 0x400800
	s_nop 0
	v_addc_co_u32_e32 v15, vcc, 0, v103, vcc
	global_load_dwordx4 v[24:27], v[102:103], off nt
	global_load_dwordx4 v[88:91], v[14:15], off nt
	v_add_co_u32_e32 v14, vcc, 0x800000, v102
	v_lshl_add_u64 v[104:105], v[102:103], 0, s[28:29]
	s_nop 0
	v_addc_co_u32_e32 v15, vcc, 0, v103, vcc
	v_add_co_u32_e32 v16, vcc, 0xc00000, v102
	s_mov_b64 s[28:29], 0x800800
	s_nop 0
	v_addc_co_u32_e32 v17, vcc, 0, v103, vcc
	global_load_dwordx4 v[92:95], v[14:15], off nt
	global_load_dwordx4 v[96:99], v[16:17], off nt
	v_lshl_add_u64 v[106:107], v[102:103], 0, s[28:29]
	s_mov_b64 s[28:29], 0xc00800
	s_mov_b64 s[4:5], -1
	s_and_b64 vcc, exec, s[38:39]
	v_lshl_add_u64 v[100:101], v[102:103], 0, s[28:29]
	s_waitcnt vmcnt(0)
	v_pk_add_f32 v[108:109], v[30:31], v[24:25]
	s_cbranch_vccnz .LBB0_514
	v_add_co_u32_e32 v126, vcc, 0x1000000, v102
	v_lshl_add_u64 v[14:15], v[102:103], 0, s[66:67]
	s_nop 0
	v_addc_co_u32_e32 v127, vcc, 0, v103, vcc
	v_add_co_u32_e32 v172, vcc, 0x1400000, v102
	global_load_dwordx4 v[18:21], v[126:127], off nt
	s_nop 0
	global_load_dwordx4 v[14:17], v[14:15], off offset:1024 nt
	v_addc_co_u32_e32 v173, vcc, 0, v103, vcc
	v_add_co_u32_e32 v28, vcc, s35, v102
	global_load_dwordx4 v[84:87], v[172:173], off nt
	global_load_dwordx4 v[22:25], v[102:103], off offset:1024 nt
	v_addc_co_u32_e32 v29, vcc, 0, v103, vcc
	v_add_co_u32_e32 v176, vcc, 0x1800000, v102
	global_load_dwordx4 v[110:113], v[28:29], off offset:1024 nt
	s_nop 0
	v_addc_co_u32_e32 v177, vcc, 0, v103, vcc
	v_add_co_u32_e32 v164, vcc, s72, v102
	global_load_dwordx4 v[114:117], v[176:177], off nt
	s_nop 0
	v_addc_co_u32_e32 v165, vcc, 0, v103, vcc
	v_add_co_u32_e32 v168, vcc, s73, v102
	global_load_dwordx4 v[118:121], v[164:165], off offset:1024 nt
	s_nop 0
	v_addc_co_u32_e32 v169, vcc, 0, v103, vcc
	global_load_dwordx4 v[122:125], v[168:169], off offset:1024 nt
	v_add_co_u32_e32 v166, vcc, 0x1c00000, v102
	v_lshl_add_u64 v[30:31], v[102:103], 0, s[80:81]
	s_nop 0
	v_addc_co_u32_e32 v167, vcc, 0, v103, vcc
	global_load_dwordx4 v[134:137], v[166:167], off nt
	global_load_dwordx4 v[138:141], v[30:31], off offset:1024 nt
	v_lshl_add_u64 v[30:31], v[102:103], 0, s[74:75]
	global_load_dwordx4 v[148:151], v[30:31], off offset:1024 nt
	v_lshl_add_u64 v[30:31], v[102:103], 0, s[84:85]
	global_load_dwordx4 v[152:155], v[30:31], off offset:1024 nt
	global_load_dwordx4 v[156:159], v[102:103], off offset:2048 nt
	global_load_dwordx4 v[160:163], v[28:29], off offset:2048 nt
	v_pk_add_f32 v[28:29], v[32:33], v[26:27]
	v_pk_add_f32 v[30:31], v[88:89], v[108:109]
	v_pk_add_f32 v[170:171], v[90:91], v[28:29]
	v_pk_add_f32 v[174:175], v[92:93], v[30:31]
	v_pk_add_f32 v[170:171], v[94:95], v[170:171]
	global_load_dwordx4 v[28:31], v[102:103], off offset:3072 nt
	v_pk_add_f32 v[174:175], v[96:97], v[174:175]
	s_mov_b64 s[4:5], 0x1000800
	s_waitcnt vmcnt(14)
	v_pk_add_f32 v[18:19], v[174:175], v[18:19]
	s_waitcnt vmcnt(12)
	v_pk_add_f32 v[18:19], v[84:85], v[18:19]
	s_waitcnt vmcnt(11)
	v_pk_add_f32 v[178:179], v[36:37], v[24:25]
	v_pk_add_f32 v[190:191], v[34:35], v[22:23]
	global_load_dwordx4 v[22:25], v[166:167], off offset:2048 nt
	s_waitcnt vmcnt(11)
	v_pk_add_f32 v[178:179], v[112:113], v[178:179]
	v_pk_add_f32 v[190:191], v[110:111], v[190:191]
	global_load_dwordx4 v[110:113], v[164:165], off offset:2048 nt
	s_waitcnt vmcnt(11)
	v_pk_add_f32 v[18:19], v[114:115], v[18:19]
	global_load_dwordx4 v[164:167], v[126:127], off offset:2048 nt
	v_pk_add_f32 v[126:127], v[98:99], v[170:171]
	global_load_dwordx4 v[168:171], v[168:169], off offset:2048 nt
	s_nop 0
	global_load_dwordx4 v[172:175], v[172:173], off offset:2048 nt
	v_pk_add_f32 v[20:21], v[126:127], v[20:21]
	s_waitcnt vmcnt(13)
	v_pk_add_f32 v[126:127], v[120:121], v[178:179]
	v_pk_add_f32 v[178:179], v[118:119], v[190:191]
	v_pk_add_f32 v[20:21], v[86:87], v[20:21]
	s_waitcnt vmcnt(12)
	v_pk_add_f32 v[84:85], v[124:125], v[126:127]
	v_pk_add_f32 v[86:87], v[122:123], v[178:179]
	v_pk_add_f32 v[20:21], v[116:117], v[20:21]
	v_pk_add_f32 v[84:85], v[16:17], v[84:85]
	v_pk_add_f32 v[86:87], v[14:15], v[86:87]
	global_load_dwordx4 v[118:121], v[176:177], off offset:2048 nt
	s_waitcnt vmcnt(12)
	v_pk_add_f32 v[16:17], v[136:137], v[20:21]
	v_pk_add_f32 v[14:15], v[134:135], v[18:19]
	s_waitcnt vmcnt(11)
	v_pk_add_f32 v[18:19], v[140:141], v[84:85]
	v_pk_add_f32 v[20:21], v[138:139], v[86:87]
	s_waitcnt vmcnt(10)
	v_pk_add_f32 v[18:19], v[150:151], v[18:19]
	v_pk_add_f32 v[84:85], v[148:149], v[20:21]
	s_waitcnt vmcnt(9)
	v_pk_add_f32 v[20:21], v[154:155], v[18:19]
	v_pk_add_f32 v[18:19], v[152:153], v[84:85]
	global_load_dwordx4 v[84:87], v[104:105], off offset:1024 nt
	global_load_dwordx4 v[114:117], v[106:107], off offset:1024 nt
	global_load_dwordx4 v[122:125], v[100:101], off offset:1024 nt
	v_lshl_add_u64 v[126:127], v[102:103], 0, s[4:5]
	s_mov_b64 s[4:5], 0x1400800
	global_load_dwordx4 v[134:137], v[126:127], off offset:1024 nt
	v_lshl_add_u64 v[126:127], v[102:103], 0, s[4:5]
	s_mov_b64 s[4:5], 0x1800800
	v_lshl_add_u64 v[148:149], v[102:103], 0, s[4:5]
	s_mov_b64 s[4:5], 0x1c00800
	global_load_dwordx4 v[138:141], v[126:127], off offset:1024 nt
	s_nop 0
	global_load_dwordx4 v[148:151], v[148:149], off offset:1024 nt
	s_waitcnt vmcnt(14)
	v_pk_add_f32 v[152:153], v[38:39], v[156:157]
	v_lshl_add_u64 v[154:155], v[102:103], 0, s[4:5]
	s_waitcnt vmcnt(13)
	v_pk_add_f32 v[156:157], v[160:161], v[152:153]
	global_load_dwordx4 v[152:155], v[154:155], off offset:1024 nt
	v_pk_add_f32 v[126:127], v[40:41], v[158:159]
	s_waitcnt vmcnt(13)
	v_pk_add_f32 v[30:31], v[82:83], v[30:31]
	v_pk_add_f32 v[28:29], v[80:81], v[28:29]
	v_pk_add_f32 v[126:127], v[162:163], v[126:127]
	s_mov_b64 s[4:5], 0
	s_waitcnt vmcnt(11)
	v_pk_add_f32 v[112:113], v[112:113], v[126:127]
	v_pk_add_f32 v[110:111], v[110:111], v[156:157]
	s_waitcnt vmcnt(9)
	v_pk_add_f32 v[112:113], v[170:171], v[112:113]
	v_pk_add_f32 v[110:111], v[168:169], v[110:111]
	v_pk_add_f32 v[112:113], v[166:167], v[112:113]
	v_pk_add_f32 v[110:111], v[164:165], v[110:111]
	s_waitcnt vmcnt(8)
	v_pk_add_f32 v[112:113], v[174:175], v[112:113]
	v_pk_add_f32 v[110:111], v[172:173], v[110:111]
	s_waitcnt vmcnt(7)
	v_pk_add_f32 v[112:113], v[120:121], v[112:113]
	v_pk_add_f32 v[110:111], v[118:119], v[110:111]
	v_pk_add_f32 v[24:25], v[24:25], v[112:113]
	v_pk_add_f32 v[22:23], v[22:23], v[110:111]
	s_waitcnt vmcnt(6)
	v_pk_add_f32 v[30:31], v[86:87], v[30:31]
	v_pk_add_f32 v[28:29], v[84:85], v[28:29]
	s_waitcnt vmcnt(5)
	v_pk_add_f32 v[30:31], v[116:117], v[30:31]
	v_pk_add_f32 v[28:29], v[114:115], v[28:29]
	s_waitcnt vmcnt(4)
	v_pk_add_f32 v[30:31], v[124:125], v[30:31]
	v_pk_add_f32 v[28:29], v[122:123], v[28:29]
	s_waitcnt vmcnt(3)
	v_pk_add_f32 v[30:31], v[136:137], v[30:31]
	v_pk_add_f32 v[28:29], v[134:135], v[28:29]
	s_waitcnt vmcnt(2)
	v_pk_add_f32 v[30:31], v[140:141], v[30:31]
	v_pk_add_f32 v[28:29], v[138:139], v[28:29]
	s_waitcnt vmcnt(1)
	v_pk_add_f32 v[30:31], v[150:151], v[30:31]
	v_pk_add_f32 v[28:29], v[148:149], v[28:29]
	s_waitcnt vmcnt(0)
	v_pk_add_f32 v[86:87], v[154:155], v[30:31]
	v_pk_add_f32 v[84:85], v[152:153], v[28:29]
.LBB0_514:
	s_andn2_b64 vcc, exec, s[4:5]
	s_cbranch_vccnz .LBB0_516
	v_pk_add_f32 v[14:15], v[32:33], v[26:27]
	v_add_co_u32_e32 v84, vcc, s35, v102
	v_pk_add_f32 v[14:15], v[90:91], v[14:15]
	v_pk_add_f32 v[16:17], v[88:89], v[108:109]
	v_addc_co_u32_e32 v85, vcc, 0, v103, vcc
	v_pk_add_f32 v[14:15], v[94:95], v[14:15]
	v_pk_add_f32 v[18:19], v[92:93], v[16:17]
	v_add_co_u32_e32 v86, vcc, s72, v102
	v_pk_add_f32 v[16:17], v[98:99], v[14:15]
	v_pk_add_f32 v[14:15], v[96:97], v[18:19]
	global_load_dwordx4 v[18:21], v[102:103], off offset:1024 nt
	v_addc_co_u32_e32 v87, vcc, 0, v103, vcc
	global_load_dwordx4 v[22:25], v[84:85], off offset:1024 nt
	global_load_dwordx4 v[26:29], v[86:87], off offset:1024 nt
	v_add_co_u32_e32 v92, vcc, s73, v102
	s_nop 1
	v_addc_co_u32_e32 v93, vcc, 0, v103, vcc
	global_load_dwordx4 v[30:33], v[92:93], off offset:1024 nt
	s_waitcnt vmcnt(3)
	v_pk_add_f32 v[20:21], v[36:37], v[20:21]
	v_pk_add_f32 v[18:19], v[34:35], v[18:19]
	s_waitcnt vmcnt(2)
	v_pk_add_f32 v[20:21], v[24:25], v[20:21]
	v_pk_add_f32 v[18:19], v[22:23], v[18:19]
	s_waitcnt vmcnt(1)
	v_pk_add_f32 v[20:21], v[28:29], v[20:21]
	v_pk_add_f32 v[18:19], v[26:27], v[18:19]
	s_waitcnt vmcnt(0)
	v_pk_add_f32 v[20:21], v[32:33], v[20:21]
	v_pk_add_f32 v[18:19], v[30:31], v[18:19]
	global_load_dwordx4 v[26:29], v[102:103], off offset:3072 nt
	global_load_dwordx4 v[22:25], v[102:103], off offset:2048 nt
	global_load_dwordx4 v[30:33], v[84:85], off offset:2048 nt
	global_load_dwordx4 v[34:37], v[104:105], off offset:1024 nt
	s_nop 0
	global_load_dwordx4 v[84:87], v[86:87], off offset:2048 nt
	s_nop 0
	global_load_dwordx4 v[88:91], v[106:107], off offset:1024 nt
	s_nop 0
	global_load_dwordx4 v[92:95], v[92:93], off offset:2048 nt
	s_nop 0
	global_load_dwordx4 v[96:99], v[100:101], off offset:1024 nt
	s_waitcnt vmcnt(7)
	v_pk_add_f32 v[28:29], v[82:83], v[28:29]
	s_waitcnt vmcnt(6)
	v_pk_add_f32 v[24:25], v[40:41], v[24:25]
	v_pk_add_f32 v[22:23], v[38:39], v[22:23]
	v_pk_add_f32 v[26:27], v[80:81], v[26:27]
	s_waitcnt vmcnt(5)
	v_pk_add_f32 v[24:25], v[32:33], v[24:25]
	v_pk_add_f32 v[22:23], v[30:31], v[22:23]
	s_waitcnt vmcnt(4)
	v_pk_add_f32 v[28:29], v[36:37], v[28:29]
	v_pk_add_f32 v[26:27], v[34:35], v[26:27]
	s_waitcnt vmcnt(3)
	v_pk_add_f32 v[24:25], v[86:87], v[24:25]
	v_pk_add_f32 v[22:23], v[84:85], v[22:23]
	s_waitcnt vmcnt(2)
	v_pk_add_f32 v[28:29], v[90:91], v[28:29]
	v_pk_add_f32 v[26:27], v[88:89], v[26:27]
	s_waitcnt vmcnt(1)
	v_pk_add_f32 v[24:25], v[94:95], v[24:25]
	v_pk_add_f32 v[22:23], v[92:93], v[22:23]
	s_waitcnt vmcnt(0)
	v_pk_add_f32 v[86:87], v[98:99], v[28:29]
	v_pk_add_f32 v[84:85], v[96:97], v[26:27]

.LBB0_519:
	s_andn2_b64 vcc, exec, s[4:5]
	s_cbranch_vccnz .LBB0_525
	s_add_i32 s4, s55, s78
	s_mov_b32 s5, s79
	v_lshl_add_u64 v[134:135], s[4:5], 2, v[130:131]
	v_add_co_u32_e32 v26, vcc, 0x400000, v134
	s_mov_b64 s[28:29], -1
	s_nop 0
	v_addc_co_u32_e32 v27, vcc, 0, v135, vcc
	global_load_dwordx4 v[36:39], v[134:135], off nt
	global_load_dwordx4 v[88:91], v[26:27], off nt
	v_add_co_u32_e32 v26, vcc, 0x800000, v134
	s_waitcnt vmcnt(0)
	v_pk_add_f32 v[2:3], v[2:3], v[36:37]
	v_addc_co_u32_e32 v27, vcc, 0, v135, vcc
	v_add_co_u32_e32 v28, vcc, 0xc00000, v134
	s_nop 1
	v_addc_co_u32_e32 v29, vcc, 0, v135, vcc
	global_load_dwordx4 v[92:95], v[26:27], off nt
	global_load_dwordx4 v[96:99], v[28:29], off nt
	s_and_b64 vcc, exec, s[38:39]
	s_mov_b64 s[38:39], 0x400800
	v_lshl_add_u64 v[136:137], v[134:135], 0, s[38:39]
	s_mov_b64 s[38:39], 0x800800
	v_lshl_add_u64 v[138:139], v[134:135], 0, s[38:39]
	s_mov_b64 s[38:39], 0xc00800
	v_lshl_add_u64 v[40:41], v[134:135], 0, s[38:39]
	s_cbranch_vccnz .LBB0_522
	v_add_co_u32_e32 v34, vcc, 0x1000000, v134
	v_lshl_add_u64 v[30:31], v[134:135], 0, s[66:67]
	s_nop 0
	v_addc_co_u32_e32 v35, vcc, 0, v135, vcc
	v_add_co_u32_e32 v36, vcc, 0x1400000, v134
	global_load_dwordx4 v[26:29], v[34:35], off nt
	s_nop 0
	global_load_dwordx4 v[30:33], v[30:31], off offset:1024 nt
	v_addc_co_u32_e32 v37, vcc, 0, v135, vcc
	v_add_co_u32_e32 v124, vcc, 0x1800000, v134
	v_lshl_add_u64 v[104:105], v[134:135], 0, s[80:81]
	s_nop 0
	v_addc_co_u32_e32 v125, vcc, 0, v135, vcc
	global_load_dwordx4 v[100:103], v[36:37], off nt
	s_nop 0
	global_load_dwordx4 v[104:107], v[104:105], off offset:1024 nt
	v_lshl_add_u64 v[112:113], v[134:135], 0, s[74:75]
	v_add_co_u32_e32 v140, vcc, 0x1c00000, v134
	global_load_dwordx4 v[108:111], v[124:125], off nt
	s_nop 0
	global_load_dwordx4 v[112:115], v[112:113], off offset:1024 nt
	v_lshl_add_u64 v[120:121], v[134:135], 0, s[84:85]
	v_addc_co_u32_e32 v141, vcc, 0, v135, vcc
	global_load_dwordx4 v[116:119], v[140:141], off nt
	s_nop 0
	global_load_dwordx4 v[120:123], v[120:121], off offset:1024 nt
	v_pk_add_f32 v[126:127], v[4:5], v[38:39]
	v_pk_add_f32 v[148:149], v[88:89], v[2:3]
	v_pk_add_f32 v[126:127], v[90:91], v[126:127]
	s_waitcnt vmcnt(9)
	v_pk_add_f32 v[148:149], v[92:93], v[148:149]
	v_pk_add_f32 v[126:127], v[94:95], v[126:127]
	s_waitcnt vmcnt(8)
	v_pk_add_f32 v[148:149], v[96:97], v[148:149]
	v_pk_add_f32 v[126:127], v[98:99], v[126:127]
	s_mov_b64 s[28:29], 0x1000800
	s_waitcnt vmcnt(7)
	v_pk_add_f32 v[28:29], v[126:127], v[28:29]
	v_add_co_u32_e32 v126, vcc, s35, v134
	v_pk_add_f32 v[26:27], v[148:149], v[26:27]
	s_nop 0
	v_addc_co_u32_e32 v127, vcc, 0, v135, vcc
	v_add_co_u32_e32 v156, vcc, s72, v134
	s_waitcnt vmcnt(5)
	v_pk_add_f32 v[28:29], v[102:103], v[28:29]
	v_pk_add_f32 v[26:27], v[100:101], v[26:27]
	global_load_dwordx4 v[100:103], v[134:135], off offset:1024 nt
	v_addc_co_u32_e32 v157, vcc, 0, v135, vcc
	s_waitcnt vmcnt(4)
	v_pk_add_f32 v[28:29], v[110:111], v[28:29]
	v_pk_add_f32 v[26:27], v[108:109], v[26:27]
	global_load_dwordx4 v[108:111], v[126:127], off offset:1024 nt
	v_add_co_u32_e32 v160, vcc, s73, v134
	s_waitcnt vmcnt(3)
	v_pk_add_f32 v[28:29], v[118:119], v[28:29]
	v_pk_add_f32 v[26:27], v[116:117], v[26:27]
	global_load_dwordx4 v[116:119], v[156:157], off offset:1024 nt
	v_addc_co_u32_e32 v161, vcc, 0, v135, vcc
	global_load_dwordx4 v[148:151], v[160:161], off offset:1024 nt
	s_waitcnt vmcnt(3)
	v_pk_add_f32 v[102:103], v[8:9], v[102:103]
	v_pk_add_f32 v[100:101], v[6:7], v[100:101]
	s_waitcnt vmcnt(2)
	v_pk_add_f32 v[102:103], v[110:111], v[102:103]
	v_pk_add_f32 v[100:101], v[108:109], v[100:101]
	s_waitcnt vmcnt(1)
	v_pk_add_f32 v[102:103], v[118:119], v[102:103]
	v_pk_add_f32 v[100:101], v[116:117], v[100:101]
	v_lshl_add_u64 v[116:117], v[134:135], 0, s[28:29]
	s_waitcnt vmcnt(0)
	v_pk_add_f32 v[102:103], v[150:151], v[102:103]
	v_pk_add_f32 v[100:101], v[148:149], v[100:101]
	v_pk_add_f32 v[32:33], v[32:33], v[102:103]
	v_pk_add_f32 v[30:31], v[30:31], v[100:101]
	v_pk_add_f32 v[32:33], v[106:107], v[32:33]
	v_pk_add_f32 v[30:31], v[104:105], v[30:31]
	v_pk_add_f32 v[32:33], v[114:115], v[32:33]
	v_pk_add_f32 v[30:31], v[112:113], v[30:31]
	global_load_dwordx4 v[100:103], v[134:135], off offset:3072 nt
	global_load_dwordx4 v[148:151], v[134:135], off offset:2048 nt
	global_load_dwordx4 v[152:155], v[126:127], off offset:2048 nt
	global_load_dwordx4 v[104:107], v[136:137], off offset:1024 nt
	s_nop 0
	global_load_dwordx4 v[156:159], v[156:157], off offset:2048 nt
	s_nop 0
	global_load_dwordx4 v[108:111], v[138:139], off offset:1024 nt
	s_nop 0
	global_load_dwordx4 v[160:163], v[160:161], off offset:2048 nt
	s_nop 0
	global_load_dwordx4 v[112:115], v[40:41], off offset:1024 nt
	s_mov_b64 s[28:29], 0x1400800
	v_pk_add_f32 v[30:31], v[120:121], v[30:31]
	global_load_dwordx4 v[164:167], v[34:35], off offset:2048 nt
	s_nop 0
	global_load_dwordx4 v[116:119], v[116:117], off offset:1024 nt
	v_lshl_add_u64 v[120:121], v[134:135], 0, s[28:29]
	s_mov_b64 s[28:29], 0x1800800
	v_pk_add_f32 v[32:33], v[122:123], v[32:33]
	global_load_dwordx4 v[34:37], v[36:37], off offset:2048 nt
	s_nop 0
	global_load_dwordx4 v[120:123], v[120:121], off offset:1024 nt
	v_lshl_add_u64 v[126:127], v[134:135], 0, s[28:29]
	s_mov_b64 s[28:29], 0x1c00800
	global_load_dwordx4 v[168:171], v[124:125], off offset:2048 nt
	s_nop 0
	global_load_dwordx4 v[124:127], v[126:127], off offset:1024 nt
	v_lshl_add_u64 v[176:177], v[134:135], 0, s[28:29]
	global_load_dwordx4 v[172:175], v[140:141], off offset:2048 nt
	s_nop 0
	global_load_dwordx4 v[176:179], v[176:177], off offset:1024 nt
	s_mov_b64 s[28:29], 0
	s_waitcnt vmcnt(15)
	v_pk_add_f32 v[102:103], v[60:61], v[102:103]
	s_waitcnt vmcnt(14)
	v_pk_add_f32 v[140:141], v[12:13], v[150:151]
	v_pk_add_f32 v[148:149], v[10:11], v[148:149]
	v_pk_add_f32 v[100:101], v[58:59], v[100:101]
	s_waitcnt vmcnt(13)
	v_pk_add_f32 v[140:141], v[154:155], v[140:141]
	v_pk_add_f32 v[148:149], v[152:153], v[148:149]
	s_waitcnt vmcnt(12)
	v_pk_add_f32 v[102:103], v[106:107], v[102:103]
	v_pk_add_f32 v[100:101], v[104:105], v[100:101]
	s_waitcnt vmcnt(11)
	v_pk_add_f32 v[140:141], v[158:159], v[140:141]
	v_pk_add_f32 v[148:149], v[156:157], v[148:149]
	s_waitcnt vmcnt(10)
	v_pk_add_f32 v[102:103], v[110:111], v[102:103]
	v_pk_add_f32 v[100:101], v[108:109], v[100:101]
	s_waitcnt vmcnt(9)
	v_pk_add_f32 v[140:141], v[162:163], v[140:141]
	v_pk_add_f32 v[148:149], v[160:161], v[148:149]
	s_waitcnt vmcnt(8)
	v_pk_add_f32 v[102:103], v[114:115], v[102:103]
	v_pk_add_f32 v[100:101], v[112:113], v[100:101]
	s_waitcnt vmcnt(7)
	v_pk_add_f32 v[140:141], v[166:167], v[140:141]
	v_pk_add_f32 v[148:149], v[164:165], v[148:149]
	s_waitcnt vmcnt(6)
	v_pk_add_f32 v[102:103], v[118:119], v[102:103]
	v_pk_add_f32 v[100:101], v[116:117], v[100:101]
	s_waitcnt vmcnt(5)
	v_pk_add_f32 v[36:37], v[36:37], v[140:141]
	v_pk_add_f32 v[34:35], v[34:35], v[148:149]
	s_waitcnt vmcnt(4)
	v_pk_add_f32 v[102:103], v[122:123], v[102:103]
	v_pk_add_f32 v[100:101], v[120:121], v[100:101]
	s_waitcnt vmcnt(3)
	v_pk_add_f32 v[36:37], v[170:171], v[36:37]
	v_pk_add_f32 v[34:35], v[168:169], v[34:35]
	s_waitcnt vmcnt(2)
	v_pk_add_f32 v[102:103], v[126:127], v[102:103]
	v_pk_add_f32 v[100:101], v[124:125], v[100:101]
	s_waitcnt vmcnt(1)
	v_pk_add_f32 v[36:37], v[174:175], v[36:37]
	v_pk_add_f32 v[34:35], v[172:173], v[34:35]
	s_waitcnt vmcnt(0)
	v_pk_add_f32 v[102:103], v[178:179], v[102:103]
	v_pk_add_f32 v[100:101], v[176:177], v[100:101]
.LBB0_522:
	s_andn2_b64 vcc, exec, s[28:29]
	s_cbranch_vccnz .LBB0_524
	v_pk_add_f32 v[4:5], v[4:5], v[38:39]
	v_add_co_u32_e32 v38, vcc, s35, v134
	v_pk_add_f32 v[4:5], v[90:91], v[4:5]
	v_pk_add_f32 v[2:3], v[88:89], v[2:3]
	v_addc_co_u32_e32 v39, vcc, 0, v135, vcc
	s_waitcnt vmcnt(1)
	v_pk_add_f32 v[4:5], v[94:95], v[4:5]
	v_pk_add_f32 v[2:3], v[92:93], v[2:3]
	v_add_co_u32_e32 v92, vcc, s72, v134
	s_waitcnt vmcnt(0)
	v_pk_add_f32 v[28:29], v[98:99], v[4:5]
	v_pk_add_f32 v[26:27], v[96:97], v[2:3]
	global_load_dwordx4 v[2:5], v[134:135], off offset:1024 nt
	v_addc_co_u32_e32 v93, vcc, 0, v135, vcc
	global_load_dwordx4 v[30:33], v[38:39], off offset:1024 nt
	global_load_dwordx4 v[34:37], v[92:93], off offset:1024 nt
	v_add_co_u32_e32 v100, vcc, s73, v134
	s_nop 1
	v_addc_co_u32_e32 v101, vcc, 0, v135, vcc
	global_load_dwordx4 v[88:91], v[100:101], off offset:1024 nt
	s_waitcnt vmcnt(3)
	v_pk_add_f32 v[4:5], v[8:9], v[4:5]
	v_pk_add_f32 v[2:3], v[6:7], v[2:3]
	s_waitcnt vmcnt(2)
	v_pk_add_f32 v[4:5], v[32:33], v[4:5]
	v_pk_add_f32 v[2:3], v[30:31], v[2:3]
	s_waitcnt vmcnt(1)
	v_pk_add_f32 v[4:5], v[36:37], v[4:5]
	v_pk_add_f32 v[2:3], v[34:35], v[2:3]
	s_waitcnt vmcnt(0)
	v_pk_add_f32 v[32:33], v[90:91], v[4:5]
	v_pk_add_f32 v[30:31], v[88:89], v[2:3]
	global_load_dwordx4 v[2:5], v[134:135], off offset:3072 nt
	global_load_dwordx4 v[6:9], v[134:135], off offset:2048 nt
	global_load_dwordx4 v[34:37], v[38:39], off offset:2048 nt
	global_load_dwordx4 v[88:91], v[136:137], off offset:1024 nt
	s_nop 0
	global_load_dwordx4 v[92:95], v[92:93], off offset:2048 nt
	s_nop 0
	global_load_dwordx4 v[96:99], v[138:139], off offset:1024 nt
	s_nop 0
	global_load_dwordx4 v[100:103], v[100:101], off offset:2048 nt
	s_nop 0
	global_load_dwordx4 v[38:41], v[40:41], off offset:1024 nt
	s_waitcnt vmcnt(7)
	v_pk_add_f32 v[4:5], v[60:61], v[4:5]
	s_waitcnt vmcnt(6)
	v_pk_add_f32 v[8:9], v[12:13], v[8:9]
	v_pk_add_f32 v[6:7], v[10:11], v[6:7]
	v_pk_add_f32 v[2:3], v[58:59], v[2:3]
	s_waitcnt vmcnt(5)
	v_pk_add_f32 v[8:9], v[36:37], v[8:9]
	v_pk_add_f32 v[6:7], v[34:35], v[6:7]
	s_waitcnt vmcnt(4)
	v_pk_add_f32 v[4:5], v[90:91], v[4:5]
	v_pk_add_f32 v[2:3], v[88:89], v[2:3]
	s_waitcnt vmcnt(3)
	v_pk_add_f32 v[8:9], v[94:95], v[8:9]
	v_pk_add_f32 v[6:7], v[92:93], v[6:7]
	s_waitcnt vmcnt(2)
	v_pk_add_f32 v[4:5], v[98:99], v[4:5]
	v_pk_add_f32 v[2:3], v[96:97], v[2:3]
	s_waitcnt vmcnt(1)
	v_pk_add_f32 v[36:37], v[102:103], v[8:9]
	v_pk_add_f32 v[34:35], v[100:101], v[6:7]
	s_waitcnt vmcnt(0)
	v_pk_add_f32 v[102:103], v[40:41], v[4:5]
	v_pk_add_f32 v[100:101], v[38:39], v[2:3]
